# MFMA/LDS interleave: differential-attention V fragment reads issued ahead of the exponential block (no hard LDS wait left between), on top of the DSA trims
# speedup vs baseline: 1.0018x; 1.0018x over previous
; #define LAS __attribute__((address_space(3)))
; __device__ __forceinline__ f32x16 mma32(const h16x8 a, const h16x8 b, const f32x16 c) { return __builtin_amdgcn_mfma_f32_32x32x16_f16(a, b, c, 0, 0, 0); }
; __device__ __forceinline__ void diff_attn_item(CParams& p, int j, int layer, LAS unsigned char* lds, int b, int h, int qb, int tid_in, int lane_in, int wave) {
;     ...
;         const float alpha = __builtin_amdgcn_exp2f(m_run - m_new);
;         const bool resc = __ballot(m_new > m_run) != 0ull;
;         float ls = 0.f;
; #pragma unroll
;         for (int sub = 0; sub < 2; ++sub)
; #pragma unroll
;             for (int i = 0; i < 16; ++i) { const float e = __builtin_amdgcn_exp2f(sc[sub][i] - m_new); sc[sub][i] = e; ls += e; }
;         ls += __shfl_xor(ls, 32);
;         l_run = l_run * alpha + ls; m_run = m_new;
;         if (resc) {
; #pragma unroll
;             for (int d = 0; d < 4; ++d)
; #pragma unroll
;                 for (int i = 0; i < 16; ++i) o[d][i] *= alpha;
;         }
; #pragma unroll
;         for (int sub = 0; sub < 2; ++sub)
; #pragma unroll
;             for (int s2 = 0; s2 < 2; ++s2) {
;                 h16x8 pf;
; #pragma unroll
;                 for (int jj = 0; jj < 8; ++jj) pf[jj] = (h16)sc[sub][8 * s2 + jj];
; #pragma unroll
;                 for (int d = 0; d < 4; ++d) {
;                     const int coff = 32 * d * 72 + ((((sub << 1) | s2) ^ d) << 4);
;                     const h16x4 lo = *(const LAS h16x4*)(Vt + vlo + coff), hi = *(const LAS h16x4*)(Vt + vhi + coff);
;                     h16x8 vf; vf[0] = lo[0]; vf[1] = lo[1]; vf[2] = lo[2]; vf[3] = lo[3]; vf[4] = hi[0]; vf[5] = hi[1]; vf[6] = hi[2]; vf[7] = hi[3];
;                     o[d] = mma32(vf, pf, o[d]);
;                 }
;             }
.LdiffA_t:
	s_waitcnt lgkmcnt(0)
	ds_read_b128 v[66:69], v215 offset:34816
	ds_read_b128 v[70:73], v215 offset:39456
	ds_read_b128 v[74:77], v215 offset:44096
	ds_read_b128 v[78:81], v215 offset:48736
	ds_read_b128 v[82:85], v215 offset:34848
	ds_read_b128 v[86:89], v215 offset:39424
	ds_read_b128 v[90:93], v215 offset:44128
	ds_read_b128 v[94:97], v215 offset:48704
	v_sub_f32_e32 v246, v201, v213
	v_pk_add_f32 v[162:163], v[162:163], v[246:247] op_sel_hi:[1,0] neg_lo:[0,1] neg_hi:[0,1]
	v_pk_add_f32 v[164:165], v[164:165], v[246:247] op_sel_hi:[1,0] neg_lo:[0,1] neg_hi:[0,1]
	v_pk_add_f32 v[166:167], v[166:167], v[246:247] op_sel_hi:[1,0] neg_lo:[0,1] neg_hi:[0,1]
	v_pk_add_f32 v[168:169], v[168:169], v[246:247] op_sel_hi:[1,0] neg_lo:[0,1] neg_hi:[0,1]
	v_pk_add_f32 v[170:171], v[170:171], v[246:247] op_sel_hi:[1,0] neg_lo:[0,1] neg_hi:[0,1]
	v_pk_add_f32 v[172:173], v[172:173], v[246:247] op_sel_hi:[1,0] neg_lo:[0,1] neg_hi:[0,1]
	v_pk_add_f32 v[174:175], v[174:175], v[246:247] op_sel_hi:[1,0] neg_lo:[0,1] neg_hi:[0,1]
	v_pk_add_f32 v[176:177], v[176:177], v[246:247] op_sel_hi:[1,0] neg_lo:[0,1] neg_hi:[0,1]
	v_pk_add_f32 v[228:229], v[228:229], v[246:247] op_sel_hi:[1,0] neg_lo:[0,1] neg_hi:[0,1]
	v_pk_add_f32 v[230:231], v[230:231], v[246:247] op_sel_hi:[1,0] neg_lo:[0,1] neg_hi:[0,1]
	v_pk_add_f32 v[232:233], v[232:233], v[246:247] op_sel_hi:[1,0] neg_lo:[0,1] neg_hi:[0,1]
	v_pk_add_f32 v[234:235], v[234:235], v[246:247] op_sel_hi:[1,0] neg_lo:[0,1] neg_hi:[0,1]
	v_pk_add_f32 v[236:237], v[236:237], v[246:247] op_sel_hi:[1,0] neg_lo:[0,1] neg_hi:[0,1]
	v_pk_add_f32 v[238:239], v[238:239], v[246:247] op_sel_hi:[1,0] neg_lo:[0,1] neg_hi:[0,1]
	v_pk_add_f32 v[240:241], v[240:241], v[246:247] op_sel_hi:[1,0] neg_lo:[0,1] neg_hi:[0,1]
	v_pk_add_f32 v[242:243], v[242:243], v[246:247] op_sel_hi:[1,0] neg_lo:[0,1] neg_hi:[0,1]
	v_exp_f32_e32 v162, v162
	v_exp_f32_e32 v163, v163
	v_exp_f32_e32 v164, v164
	v_exp_f32_e32 v165, v165
	v_exp_f32_e32 v166, v166
	v_exp_f32_e32 v167, v167
	v_exp_f32_e32 v168, v168
	v_exp_f32_e32 v169, v169
	v_exp_f32_e32 v170, v170
	v_exp_f32_e32 v171, v171
	v_exp_f32_e32 v172, v172
	v_exp_f32_e32 v173, v173
	v_exp_f32_e32 v174, v174
	v_exp_f32_e32 v175, v175
	v_exp_f32_e32 v176, v176
	v_exp_f32_e32 v177, v177
	v_exp_f32_e32 v228, v228
	v_exp_f32_e32 v229, v229
	v_exp_f32_e32 v230, v230
	v_exp_f32_e32 v231, v231
	v_exp_f32_e32 v232, v232
	v_exp_f32_e32 v233, v233
	v_exp_f32_e32 v234, v234
	v_exp_f32_e32 v235, v235
	v_exp_f32_e32 v236, v236
	v_exp_f32_e32 v237, v237
	v_exp_f32_e32 v238, v238
	v_exp_f32_e32 v239, v239
	v_exp_f32_e32 v240, v240
	v_exp_f32_e32 v241, v241
	v_exp_f32_e32 v242, v242
	v_exp_f32_e32 v243, v243
	v_pk_add_f32 v[250:251], v[162:163], v[164:165]
	v_pk_add_f32 v[250:251], v[250:251], v[166:167]
	v_pk_add_f32 v[250:251], v[250:251], v[168:169]
	v_pk_add_f32 v[250:251], v[250:251], v[170:171]
	v_pk_add_f32 v[250:251], v[250:251], v[172:173]
	v_pk_add_f32 v[250:251], v[250:251], v[174:175]
	v_pk_add_f32 v[250:251], v[250:251], v[176:177]
	v_pk_add_f32 v[250:251], v[250:251], v[228:229]
	v_pk_add_f32 v[250:251], v[250:251], v[230:231]
	v_pk_add_f32 v[250:251], v[250:251], v[232:233]
	v_pk_add_f32 v[250:251], v[250:251], v[234:235]
	v_pk_add_f32 v[250:251], v[250:251], v[236:237]
	v_pk_add_f32 v[250:251], v[250:251], v[238:239]
	v_pk_add_f32 v[250:251], v[250:251], v[240:241]
	v_pk_add_f32 v[250:251], v[250:251], v[242:243]
	s_nop 0
	v_add_f32_e32 v250, v250, v251
	v_cvt_pk_f16_f32 v144, v162, v163
	v_cvt_pk_f16_f32 v145, v164, v165
	v_cvt_pk_f16_f32 v146, v166, v167
	v_cvt_pk_f16_f32 v147, v168, v169
	v_cvt_pk_f16_f32 v148, v170, v171
	v_cvt_pk_f16_f32 v149, v172, v173
	v_cvt_pk_f16_f32 v150, v174, v175
	v_cvt_pk_f16_f32 v151, v176, v177
	v_cvt_pk_f16_f32 v152, v228, v229
	v_cvt_pk_f16_f32 v153, v230, v231
	v_cvt_pk_f16_f32 v154, v232, v233
	v_cvt_pk_f16_f32 v155, v234, v235
	v_cvt_pk_f16_f32 v178, v236, v237
	v_cvt_pk_f16_f32 v179, v238, v239
	v_cvt_pk_f16_f32 v180, v240, v241
	v_cvt_pk_f16_f32 v181, v242, v243
	s_cmp_lg_u32 s101, 0
	s_cbranch_scc1 .LdiffA_ok
	v_cmp_nge_f32_e32 vcc, 0x43800000, v250
	s_cbranch_vccz .LdiffA_ok
	s_mov_b32 s100, 0
	s_mov_b32 s101, 1
	s_branch .LdiffA_top
.LdiffA_ok:
	v_add_f32_e32 v197, v197, v250
	s_waitcnt lgkmcnt(4)
	v_mfma_f32_32x32x16_f16 v[50:65], v[66:69], v[144:147], v[50:65]
	v_mfma_f32_32x32x16_f16 v[34:49], v[70:73], v[144:147], v[34:49]
	v_mfma_f32_32x32x16_f16 v[18:33], v[74:77], v[144:147], v[18:33]
	v_mfma_f32_32x32x16_f16 v[2:17], v[78:81], v[144:147], v[2:17]
	ds_read_b128 v[66:69], v215 offset:34880
	ds_read_b128 v[70:73], v215 offset:39520
	ds_read_b128 v[74:77], v215 offset:44032
	ds_read_b128 v[78:81], v215 offset:48672
	s_waitcnt lgkmcnt(4)
	v_mfma_f32_32x32x16_f16 v[50:65], v[82:85], v[148:151], v[50:65]
	v_mfma_f32_32x32x16_f16 v[34:49], v[86:89], v[148:151], v[34:49]
	v_mfma_f32_32x32x16_f16 v[18:33], v[90:93], v[148:151], v[18:33]
	v_mfma_f32_32x32x16_f16 v[2:17], v[94:97], v[148:151], v[2:17]
	ds_read_b128 v[82:85], v215 offset:34912
	ds_read_b128 v[86:89], v215 offset:39488
	ds_read_b128 v[90:93], v215 offset:44064
	ds_read_b128 v[94:97], v215 offset:48640
	s_waitcnt lgkmcnt(4)
	v_mfma_f32_32x32x16_f16 v[50:65], v[66:69], v[152:155], v[50:65]
	v_mfma_f32_32x32x16_f16 v[34:49], v[70:73], v[152:155], v[34:49]
	v_mfma_f32_32x32x16_f16 v[18:33], v[74:77], v[152:155], v[18:33]
	v_mfma_f32_32x32x16_f16 v[2:17], v[78:81], v[152:155], v[2:17]
	s_waitcnt lgkmcnt(0)
	v_mfma_f32_32x32x16_f16 v[50:65], v[82:85], v[178:181], v[50:65]
	v_mfma_f32_32x32x16_f16 v[34:49], v[86:89], v[178:181], v[34:49]
	v_mfma_f32_32x32x16_f16 v[18:33], v[90:93], v[178:181], v[18:33]
	v_mfma_f32_32x32x16_f16 v[2:17], v[94:97], v[178:181], v[2:17]
	s_branch .LdiffA_end
